# k_rope item loop: the W_kr operand fragments are loaded once in front of the loop instead of once per item
# baseline (speedup 1.0000x reference)
; #define LAS __attribute__((address_space(3)))
; DI void krope_phase(const Frame& F, int crank, int ncu) {
;     const bf16_t* H = (const bf16_t*)(F.ws + WS_HB); const bf16_t* Wk = (const bf16_t*)(F.ws + WS_W + W_KR); bf16_t* KR = (bf16_t*)(F.ws + WS_KR);
;     const float* rm = (const float*)(F.ws + WS_ROPEM);
;     const int r32 = F.lane & 31, h5 = F.lane >> 5, w = F.wave;
;     LAS float* part = (LAS float*)F.lds;
;     for (int it = crank; it < MT / 32; it += ncu) {
;         const int row0 = it * 32;
;         f32x16 acc;
; #pragma unroll
;         for (int i = 0; i < 16; ++i) acc[i] = 0.f;
;         const bf16_t* hp = H + (size_t)(row0 + r32) * 1024 + 8 * h5 + 128 * w; const bf16_t* wp = Wk + (size_t)r32 * 1024 + 8 * h5 + 128 * w;
;         bf16x8 a[8], b[8];
; #pragma unroll
;         for (int q = 0; q < 8; ++q) { a[q] = *(const bf16x8*)(wp + 16 * q); b[q] = *(const bf16x8*)(hp + 16 * q); }
.LBB0_537:
	s_andn2_b64 vcc, exec, s[60:61]
	s_cbranch_vccnz .LBB0_662
	s_cmpk_gt_u32 s96, 0x23f
	s_cbranch_scc1 .LBB0_575
	v_lshrrev_b32_e32 v0, 5, v186
	s_add_u32 s6, s94, 0x200000
	v_lshlrev_b32_e32 v96, 3, v0
	v_lshlrev_b32_e32 v0, 4, v0
	v_mov_b32_e32 v1, v97
	v_readlane_b32 s4, v255, 31
	s_addc_u32 s7, s95, 0
	v_lshl_add_u64 v[2:3], s[94:95], 0, v[0:1]
	s_lshl_b32 s16, s4, 8
	v_and_b32_e32 v4, 31, v225
	v_lshl_add_u64 v[2:3], v[2:3], 0, s[16:17]
	s_mov_b64 s[2:3], 0x3e00000
	v_lshl_add_u64 v[16:17], v[2:3], 0, s[2:3]
	v_lshlrev_b32_e32 v2, 11, v4
	v_mov_b32_e32 v3, v97
	v_lshl_add_u64 v[2:3], s[94:95], 0, v[2:3]
	v_lshl_add_u64 v[0:1], v[2:3], 0, v[0:1]
	v_lshl_add_u64 v[0:1], v[0:1], 0, s[16:17]
	s_mov_b64 s[2:3], 0x1d80000
	v_lshl_add_u64 v[18:19], v[0:1], 0, s[2:3]
	s_lshl_b32 s2, s4, 12
	v_lshl_add_u64 v[0:1], s[94:95], 0, v[96:97]
	s_mov_b64 s[4:5], 0x8f00000
	s_add_i32 s10, s2, 0
	v_readlane_b32 s2, v255, 32
	v_lshl_add_u64 v[20:21], v[0:1], 0, s[4:5]
	v_lshlrev_b32_e32 v0, 2, v186
	s_cmp_lt_u32 s2, 64
	v_add_u32_e32 v22, s10, v0
	v_add_u32_e32 v23, 0, v0
	v_xor_b32_e32 v24, 0x80, v0
	v_lshlrev_b32_e32 v0, 5, v4
	s_cselect_b64 s[8:9], -1, 0
	v_cmp_gt_u32_e64 s[2:3], 32, v186
	v_lshl_or_b32 v96, s96, 5, v4
	s_lshl_b32 s12, s93, 5
	v_lshl_or_b32 v25, s96, 10, v0
	s_lshl_b32 s13, s93, 10
	s_mov_b32 s14, s96
	global_load_dwordx4 v[100:103], v[18:19], off
	global_load_dwordx4 v[104:107], v[18:19], off offset:32
	global_load_dwordx4 v[108:111], v[18:19], off offset:64
	global_load_dwordx4 v[112:115], v[18:19], off offset:96
	global_load_dwordx4 v[116:119], v[18:19], off offset:128
	global_load_dwordx4 v[120:123], v[18:19], off offset:160
	global_load_dwordx4 v[124:127], v[18:19], off offset:192
	global_load_dwordx4 v[128:131], v[18:19], off offset:224
	s_branch .LBB0_542

; #define MFMA32(a, b, c) __builtin_amdgcn_mfma_f32_32x32x16_bf16((a), (b), (c), 0, 0, 0)
; DI void krope_phase(const Frame& F, int crank, int ncu) {
;     ...
;         const bf16_t* hp = H + (size_t)(row0 + r32) * 1024 + 8 * h5 + 128 * w; const bf16_t* wp = Wk + (size_t)r32 * 1024 + 8 * h5 + 128 * w;
;         bf16x8 a[8], b[8];
; #pragma unroll
;         for (int q = 0; q < 8; ++q) { a[q] = *(const bf16x8*)(wp + 16 * q); b[q] = *(const bf16x8*)(hp + 16 * q); }
; #pragma unroll
;         for (int q = 0; q < 8; ++q) acc = MFMA32(a[q], b[q], acc);
;         __syncthreads();
; #pragma unroll
;         for (int i = 0; i < 16; ++i) part[(w * 16 + i) * 64 + F.lane] = acc[i];
;         __syncthreads();
;         if (w == 0) {
; #pragma unroll
;             for (int i = 0; i < 16; ++i) { float sacc = 0.f;
; #pragma unroll
;                 for (int q = 0; q < 8; ++q) sacc += part[(q * 16 + i) * 64 + F.lane];
;                 acc[i] = sacc; }
.LBB0_542:
	v_lshlrev_b64 v[4:5], 11, v[96:97]
	v_lshl_add_u64 v[38:39], v[16:17], 0, v[4:5]
	global_load_dwordx4 v[132:135], v[38:39], off
	global_load_dwordx4 v[136:139], v[38:39], off offset:32
	global_load_dwordx4 v[140:143], v[38:39], off offset:64
	global_load_dwordx4 v[144:147], v[38:39], off offset:96
	global_load_dwordx4 v[148:151], v[38:39], off offset:128
	global_load_dwordx4 v[152:155], v[38:39], off offset:160
	global_load_dwordx4 v[156:159], v[38:39], off offset:192
	global_load_dwordx4 v[160:163], v[38:39], off offset:224
	s_andn2_b64 vcc, exec, s[8:9]
	s_waitcnt vmcnt(7)
	v_mfma_f32_32x32x16_bf16 v[0:15], v[100:103], v[132:135], 0
	s_waitcnt vmcnt(6)
	v_mfma_f32_32x32x16_bf16 v[0:15], v[104:107], v[136:139], v[0:15]
	s_waitcnt vmcnt(5)
	v_mfma_f32_32x32x16_bf16 v[0:15], v[108:111], v[140:143], v[0:15]
	s_waitcnt vmcnt(4)
	v_mfma_f32_32x32x16_bf16 v[0:15], v[112:115], v[144:147], v[0:15]
	s_waitcnt vmcnt(3)
	v_mfma_f32_32x32x16_bf16 v[0:15], v[116:119], v[148:151], v[0:15]
	s_waitcnt vmcnt(2)
	v_mfma_f32_32x32x16_bf16 v[0:15], v[120:123], v[152:155], v[0:15]
	s_waitcnt vmcnt(1)
	v_mfma_f32_32x32x16_bf16 v[0:15], v[124:127], v[156:159], v[0:15]
	s_waitcnt vmcnt(0)
	v_mfma_f32_32x32x16_bf16 v[0:15], v[128:131], v[160:163], v[0:15]
	s_waitcnt lgkmcnt(0)
	s_barrier
	s_nop 11
	ds_write2st64_b32 v22, v0, v1 offset1:1
	ds_write2st64_b32 v22, v2, v3 offset0:2 offset1:3
	ds_write2st64_b32 v22, v4, v5 offset0:4 offset1:5
	ds_write2st64_b32 v22, v6, v7 offset0:6 offset1:7
	ds_write2st64_b32 v22, v8, v9 offset0:8 offset1:9
	ds_write2st64_b32 v22, v10, v11 offset0:10 offset1:11
	ds_write2st64_b32 v22, v12, v13 offset0:12 offset1:13
	ds_write2st64_b32 v22, v14, v15 offset0:14 offset1:15
	s_waitcnt lgkmcnt(0)
	s_barrier
	s_cbranch_vccnz .LBB0_541
	ds_read2st64_b32 v[0:1], v23 offset1:1
	ds_read2st64_b32 v[2:3], v23 offset0:16 offset1:17
	ds_read2st64_b32 v[4:5], v23 offset0:2 offset1:3
	ds_read2st64_b32 v[6:7], v23 offset0:4 offset1:5
	ds_read2st64_b32 v[8:9], v23 offset0:6 offset1:7
	s_waitcnt lgkmcnt(4)
	v_add_f32_e32 v0, 0, v0
	ds_read2st64_b32 v[10:11], v23 offset0:18 offset1:19
	ds_read2st64_b32 v[12:13], v23 offset0:20 offset1:21
	ds_read2st64_b32 v[14:15], v23 offset0:22 offset1:23
	s_waitcnt lgkmcnt(6)
	v_add_f32_e32 v0, v0, v2
	ds_read2st64_b32 v[26:27], v23 offset0:32 offset1:33
	ds_read2st64_b32 v[28:29], v23 offset0:48 offset1:49
	ds_read2st64_b32 v[30:31], v23 offset0:34 offset1:35
	ds_read2st64_b32 v[32:33], v23 offset0:36 offset1:37
	ds_read2st64_b32 v[34:35], v23 offset0:38 offset1:39
	s_waitcnt lgkmcnt(4)
	v_add_f32_e32 v0, v0, v26
	ds_read2st64_b32 v[36:37], v23 offset0:50 offset1:51
	ds_read2st64_b32 v[38:39], v23 offset0:52 offset1:53
	ds_read2st64_b32 v[40:41], v23 offset0:54 offset1:55
	s_waitcnt lgkmcnt(6)
	v_add_f32_e32 v0, v0, v28
	ds_read2st64_b32 v[42:43], v23 offset0:64 offset1:65
	ds_read2st64_b32 v[44:45], v23 offset0:80 offset1:81
	ds_read2st64_b32 v[46:47], v23 offset0:66 offset1:67
	ds_read2st64_b32 v[48:49], v23 offset0:68 offset1:69
	ds_read2st64_b32 v[50:51], v23 offset0:70 offset1:71
	s_waitcnt lgkmcnt(4)
	v_add_f32_e32 v0, v0, v42
	ds_read2st64_b32 v[52:53], v23 offset0:82 offset1:83
	ds_read2st64_b32 v[54:55], v23 offset0:84 offset1:85
	ds_read2st64_b32 v[56:57], v23 offset0:86 offset1:87
	s_waitcnt lgkmcnt(6)
	v_add_f32_e32 v0, v0, v44
	ds_read2st64_b32 v[58:59], v23 offset0:96 offset1:97
	ds_read2st64_b32 v[60:61], v23 offset0:112 offset1:113
	ds_read2st64_b32 v[62:63], v23 offset0:98 offset1:99
	ds_read2st64_b32 v[64:65], v23 offset0:100 offset1:101
	ds_read2st64_b32 v[66:67], v23 offset0:102 offset1:103
	s_waitcnt lgkmcnt(4)
	v_add_f32_e32 v0, v0, v58
	s_waitcnt lgkmcnt(3)
	v_add_f32_e32 v2, v0, v60
	v_add_f32_e32 v0, 0, v1
	v_add_f32_e32 v0, v0, v3
	v_add_f32_e32 v0, v0, v27
	v_add_f32_e32 v0, v0, v29
	v_add_f32_e32 v0, v0, v43
	v_add_f32_e32 v0, v0, v45
	v_add_f32_e32 v0, v0, v59
	v_add_f32_e32 v3, v0, v61
	v_add_f32_e32 v0, 0, v4
	v_add_f32_e32 v0, v0, v10
	v_add_f32_e32 v0, v0, v30
	v_add_f32_e32 v0, v0, v36
	ds_read2st64_b32 v[68:69], v23 offset0:114 offset1:115
	ds_read2st64_b32 v[70:71], v23 offset0:116 offset1:117
	ds_read2st64_b32 v[72:73], v23 offset0:118 offset1:119
	v_add_f32_e32 v0, v0, v46
	v_add_f32_e32 v0, v0, v52
	s_waitcnt lgkmcnt(5)
	v_add_f32_e32 v0, v0, v62
	s_waitcnt lgkmcnt(2)
	v_add_f32_e32 v4, v0, v68
	v_add_f32_e32 v0, 0, v5
	v_add_f32_e32 v0, v0, v11
	v_add_f32_e32 v0, v0, v31
	v_add_f32_e32 v0, v0, v37
	v_add_f32_e32 v0, v0, v47
	v_add_f32_e32 v0, v0, v53
	v_add_f32_e32 v0, v0, v63
	v_add_f32_e32 v5, v0, v69
	v_add_f32_e32 v0, 0, v6
	v_add_f32_e32 v0, v0, v12
	v_add_f32_e32 v0, v0, v32
	v_add_f32_e32 v0, v0, v38
	v_add_f32_e32 v0, v0, v48
	v_add_f32_e32 v0, v0, v54
	v_add_f32_e32 v0, v0, v64
	s_waitcnt lgkmcnt(1)
	v_add_f32_e32 v6, v0, v70
	v_add_f32_e32 v0, 0, v7
	v_add_f32_e32 v0, v0, v13
	v_add_f32_e32 v0, v0, v33
	v_add_f32_e32 v0, v0, v39
	v_add_f32_e32 v0, v0, v49
	v_add_f32_e32 v0, v0, v55
	v_add_f32_e32 v0, v0, v65
	v_add_f32_e32 v7, v0, v71
	v_add_f32_e32 v0, 0, v8
	v_add_f32_e32 v0, v0, v14
	v_add_f32_e32 v0, v0, v34
	v_add_f32_e32 v0, v0, v40
	v_add_f32_e32 v0, v0, v50
	v_add_f32_e32 v0, v0, v56
	v_add_f32_e32 v0, v0, v66
	s_waitcnt lgkmcnt(0)
; DI float shx(float v, int m, int lane) { return __int_as_float(__builtin_amdgcn_ds_bpermute((lane ^ m) << 2, __float_as_int(v))); }
; DI void krope_phase(const Frame& F, int crank, int ncu) {
;     ...
;         if (w == 0) {
; #pragma unroll
;             for (int i = 0; i < 16; ++i) { float sacc = 0.f;
; #pragma unroll
;                 for (int q = 0; q < 8; ++q) sacc += part[(q * 16 + i) * 64 + F.lane];
;                 acc[i] = sacc; }
;             const int row = row0 + r32;
;             f32x16 oth;
; #pragma unroll
;             for (int i = 0; i < 16; ++i) oth[i] = shx(acc[i], 32, F.lane);
;             u32x2 wv[4];
; #pragma unroll
;             for (int g = 0; g < 4; ++g) { float o[4];
; #pragma unroll
;                 for (int e = 0; e < 4; ++e) { const int i = 4 * g + e; float x1 = h5 ? oth[i] : acc[i], x2 = h5 ? acc[i] : oth[i]; float cs = 1.f, sn = 0.f;
;                     if (row < ML) { cs = rm[(size_t)(row & 2047) * 32 + i]; sn = rm[(size_t)(row & 2047) * 32 + 16 + i]; }
	v_add_f32_e32 v8, v0, v72
	v_add_f32_e32 v0, 0, v9
	v_add_f32_e32 v0, v0, v15
	v_add_f32_e32 v0, v0, v35
	v_add_f32_e32 v0, v0, v41
	v_add_f32_e32 v0, v0, v51
	v_add_f32_e32 v0, v0, v57
	v_add_f32_e32 v0, v0, v67
	v_add_f32_e32 v9, v0, v73
	ds_read2st64_b32 v[0:1], v23 offset0:8 offset1:9
	ds_read2st64_b32 v[10:11], v23 offset0:24 offset1:25
	ds_read2st64_b32 v[26:27], v23 offset0:10 offset1:11
	ds_read2st64_b32 v[28:29], v23 offset0:12 offset1:13
	ds_read2st64_b32 v[30:31], v23 offset0:14 offset1:15
	s_waitcnt lgkmcnt(4)
	v_add_f32_e32 v0, 0, v0
	ds_read2st64_b32 v[34:35], v23 offset0:26 offset1:27
	ds_read2st64_b32 v[36:37], v23 offset0:28 offset1:29
	ds_read2st64_b32 v[38:39], v23 offset0:30 offset1:31
	s_waitcnt lgkmcnt(6)
	v_add_f32_e32 v0, v0, v10
	ds_read2st64_b32 v[14:15], v23 offset0:40 offset1:41
	ds_read2st64_b32 v[32:33], v23 offset0:56 offset1:57
	ds_read2st64_b32 v[40:41], v23 offset0:42 offset1:43
	ds_read2st64_b32 v[42:43], v23 offset0:44 offset1:45
	ds_read2st64_b32 v[44:45], v23 offset0:46 offset1:47
	s_waitcnt lgkmcnt(4)
	v_add_f32_e32 v0, v0, v14
	ds_read2st64_b32 v[46:47], v23 offset0:58 offset1:59
	ds_read2st64_b32 v[48:49], v23 offset0:60 offset1:61
	ds_read2st64_b32 v[50:51], v23 offset0:62 offset1:63
	s_waitcnt lgkmcnt(6)
	v_add_f32_e32 v0, v0, v32
	ds_read2st64_b32 v[52:53], v23 offset0:72 offset1:73
	ds_read2st64_b32 v[54:55], v23 offset0:88 offset1:89
	ds_read2st64_b32 v[56:57], v23 offset0:74 offset1:75
	ds_read2st64_b32 v[58:59], v23 offset0:76 offset1:77
	ds_read2st64_b32 v[60:61], v23 offset0:78 offset1:79
	s_waitcnt lgkmcnt(4)
	v_add_f32_e32 v0, v0, v52
	ds_read2st64_b32 v[62:63], v23 offset0:90 offset1:91
	ds_read2st64_b32 v[64:65], v23 offset0:92 offset1:93
	ds_read2st64_b32 v[66:67], v23 offset0:94 offset1:95
	s_waitcnt lgkmcnt(6)
	v_add_f32_e32 v0, v0, v54
	ds_read2st64_b32 v[68:69], v23 offset0:104 offset1:105
	ds_read2st64_b32 v[70:71], v23 offset0:120 offset1:121
	ds_read2st64_b32 v[72:73], v23 offset0:106 offset1:107
	ds_read2st64_b32 v[74:75], v23 offset0:108 offset1:109
	ds_read2st64_b32 v[76:77], v23 offset0:110 offset1:111
	s_waitcnt lgkmcnt(4)
	v_add_f32_e32 v0, v0, v68
	s_waitcnt lgkmcnt(3)
	v_add_f32_e32 v13, v0, v70
	v_add_f32_e32 v0, 0, v1
	v_add_f32_e32 v0, v0, v11
	v_add_f32_e32 v0, v0, v15
	v_add_f32_e32 v0, v0, v33
	v_add_f32_e32 v0, v0, v53
	v_add_f32_e32 v0, v0, v55
	v_add_f32_e32 v0, v0, v69
	v_add_f32_e32 v14, v0, v71
	v_add_f32_e32 v0, 0, v26
	v_add_f32_e32 v0, v0, v34
	v_add_f32_e32 v0, v0, v40
	v_add_f32_e32 v0, v0, v46
	ds_read2st64_b32 v[78:79], v23 offset0:122 offset1:123
	ds_read2st64_b32 v[80:81], v23 offset0:124 offset1:125
	ds_read2st64_b32 v[82:83], v23 offset0:126 offset1:127
	v_add_f32_e32 v0, v0, v56
	v_add_f32_e32 v0, v0, v62
	s_waitcnt lgkmcnt(5)
	v_add_f32_e32 v0, v0, v72
	s_waitcnt lgkmcnt(2)
	v_add_f32_e32 v33, v0, v78
	v_add_f32_e32 v0, 0, v27
	v_add_f32_e32 v0, v0, v35
	v_add_f32_e32 v0, v0, v41
	v_add_f32_e32 v0, v0, v47
	v_add_f32_e32 v0, v0, v57
	v_add_f32_e32 v0, v0, v63
	v_add_f32_e32 v0, v0, v73
	v_add_f32_e32 v34, v0, v79
	v_add_f32_e32 v0, 0, v28
	v_add_f32_e32 v0, v0, v36
	v_add_f32_e32 v0, v0, v42
	v_add_f32_e32 v0, v0, v48
	v_add_f32_e32 v0, v0, v58
	v_add_f32_e32 v0, v0, v64
	v_add_f32_e32 v0, v0, v74
	s_waitcnt lgkmcnt(1)
	v_add_f32_e32 v40, v0, v80
	v_add_f32_e32 v0, 0, v29
	v_add_f32_e32 v0, v0, v37
	v_add_f32_e32 v0, v0, v43
	v_add_f32_e32 v0, v0, v49
	v_add_f32_e32 v0, v0, v59
	v_add_f32_e32 v0, v0, v65
	v_add_f32_e32 v0, v0, v75
	v_add_f32_e32 v41, v0, v81
	v_add_f32_e32 v0, 0, v30
	v_add_f32_e32 v0, v0, v38
	v_add_f32_e32 v0, v0, v44
	v_add_f32_e32 v0, v0, v50
	v_add_f32_e32 v0, v0, v60
	v_add_f32_e32 v0, v0, v66
	v_add_f32_e32 v0, v0, v76
	s_waitcnt lgkmcnt(0)
	v_add_f32_e32 v46, v0, v82
	v_add_f32_e32 v0, 0, v31
	v_add_f32_e32 v0, v0, v39
	v_add_f32_e32 v0, v0, v45
	v_add_f32_e32 v0, v0, v51
	v_add_f32_e32 v0, v0, v61
	v_add_f32_e32 v0, v0, v67
	v_add_f32_e32 v0, v0, v77
	v_add_f32_e32 v47, v0, v83
	ds_bpermute_b32 v11, v24, v2
	ds_bpermute_b32 v10, v24, v3
	ds_bpermute_b32 v15, v24, v4
	ds_bpermute_b32 v12, v24, v5
	ds_bpermute_b32 v35, v24, v6
	ds_bpermute_b32 v29, v24, v7
	ds_bpermute_b32 v37, v24, v8
	ds_bpermute_b32 v36, v24, v9
	ds_bpermute_b32 v43, v24, v13
	ds_bpermute_b32 v42, v24, v14
	ds_bpermute_b32 v45, v24, v33
	ds_bpermute_b32 v44, v24, v34
	ds_bpermute_b32 v51, v24, v40
	ds_bpermute_b32 v48, v24, v41
	ds_bpermute_b32 v54, v24, v46
	ds_bpermute_b32 v52, v24, v47
	v_and_b32_e32 v0, 0xffe0, v25
	s_cmpk_lt_u32 s14, 0x200
	v_lshlrev_b32_e32 v0, 2, v0
	v_mov_b32_e32 v1, v97
	s_cselect_b64 s[10:11], -1, 0
	s_cmpk_gt_u32 s14, 0x1ff
	v_lshl_add_u64 v[0:1], s[6:7], 0, v[0:1]
	v_mov_b32_e32 v30, 0
	v_mov_b32_e32 v26, 1.0
	v_mov_b32_e32 v27, 1.0
	v_mov_b32_e32 v28, 0
	s_cbranch_scc1 .LBB0_545
	global_load_dword v27, v[0:1], off
	global_load_dword v28, v[0:1], off offset:64
